# v48: v45 + channel-DFT staging with coalesced 512-B row loads into XOR-swizzled row-major LDS tiles (b128 writes), operand reads via swizzled addresses
# speedup vs baseline: 1.0046x; 1.0020x over previous
; __device__ __forceinline__ void phase_prep(const Params& P, int l, unsigned char* lds) {
;     ...
;             float* U = (float*)lds;
;             float* U2 = U + 64 * 256;
; #pragma unroll
;             for (int rep = 0; rep < 4; ++rep) {
;                 const int id = tid + 512 * rep, tok = id >> 5, ch = id & 31;
;                 const u32x4 w = *(const u32x4*)(proj + (size_t)(r0 + tok) * INW + PD_U + 8 * ch);
;                 f32x4 a0 = (f32x4){bflo(w.x), bfhi(w.x), bflo(w.y), bfhi(w.y)}, a1 = (f32x4){bflo(w.z), bfhi(w.z), bflo(w.w), bfhi(w.w)};
;                 float* d = U + tok * 256 + 8 * ch;
;                 if (!is_ctx) {
;                     const int tg = t0 - CTX + tok, mt = (tg == 0) ? SEQ / 2 : SEQ - tg;
;                     const u32x4 m = *(const u32x4*)(proj + ((size_t)b * TT + CTX + mt) * INW + PD_U + 8 * ch);
;                     const f32x4 m0 = (f32x4){bflo(m.x), bfhi(m.x), bflo(m.y), bfhi(m.y)}, m1 = (f32x4){bflo(m.z), bfhi(m.z), bflo(m.w), bfhi(m.w)};
;                     float* d2 = U2 + tok * 256 + 8 * ch;
;                     if (tg == 0) { *(f32x4*)d2 = m0; *(f32x4*)(d2 + 4) = m1; }
;                     else { *(f32x4*)d2 = a0 - m0; *(f32x4*)(d2 + 4) = a1 - m1; a0 = a0 + m0; a1 = a1 + m1; }
;                 }
;                 *(f32x4*)d = a0; *(f32x4*)(d + 4) = a1;
;     ...
;                 for (int q = 0; q < 4; ++q) { const float rev = (float)((c * (cp0 + q)) & 63) * (1.0f / 64.0f); cv[q] = __builtin_amdgcn_cosf(rev) * 0.125f; sv[q] = __builtin_amdgcn_sinf(rev) * 0.125f; }
.LBB0_232:
	s_cmpk_gt_i32 s64, 0xff
	s_cselect_b64 s[42:43], -1, 0
	s_cmpk_lt_i32 s64, 0x100
	s_cselect_b64 s[48:49], -1, 0
	s_andn2_b64 vcc, exec, s[38:39]
	s_mov_b64 s[38:39], -1
	s_cbranch_vccnz .LBB0_277
	v_and_b32_e32 v32, 63, v44
	v_lshrrev_b32_e32 v33, 5, v32
	v_and_b32_e32 v34, 31, v32
	v_readfirstlane_b32 s12, v44
	s_nop 3
	s_lshr_b32 s12, s12, 6
	s_and_b32 s13, s12, 1
	s_lshr_b32 s15, s12, 1
	v_and_b32_e32 v108, 31, v44
	v_mov_b64_e32 v[100:101], s[10:11]
	s_mul_i32 s18, s36, 0x900
	s_add_u32 s7, s18, 0x100
	v_lshrrev_b32_e32 v109, 5, v44
	v_add_u32_e32 v41, s29, v109
	v_mad_u64_u32 v[102:103], s[18:19], v41, s23, v[100:101]
	v_lshlrev_b32_e32 v42, 4, v108
	v_add_u32_e32 v42, 0x1400, v42
	v_add_co_u32_e32 v102, vcc, v102, v42
	s_nop 1
	v_addc_co_u32_e32 v103, vcc, 0, v103, vcc
	global_load_dwordx4 v[0:3], v[102:103], off
	v_lshrrev_b32_e32 v109, 5, v44
	v_add_u32_e32 v109, 16, v109
	v_add_u32_e32 v41, s29, v109
	v_mad_u64_u32 v[102:103], s[18:19], v41, s23, v[100:101]
	v_lshlrev_b32_e32 v42, 4, v108
	v_add_u32_e32 v42, 0x1400, v42
	v_add_co_u32_e32 v102, vcc, v102, v42
	s_nop 1
	v_addc_co_u32_e32 v103, vcc, 0, v103, vcc
	global_load_dwordx4 v[4:7], v[102:103], off
	v_lshrrev_b32_e32 v109, 5, v44
	v_add_u32_e32 v109, 32, v109
	v_add_u32_e32 v41, s29, v109
	v_mad_u64_u32 v[102:103], s[18:19], v41, s23, v[100:101]
	v_lshlrev_b32_e32 v42, 4, v108
	v_add_u32_e32 v42, 0x1400, v42
	v_add_co_u32_e32 v102, vcc, v102, v42
	s_nop 1
	v_addc_co_u32_e32 v103, vcc, 0, v103, vcc
	global_load_dwordx4 v[8:11], v[102:103], off
	v_lshrrev_b32_e32 v109, 5, v44
	v_add_u32_e32 v109, 48, v109
	v_add_u32_e32 v41, s29, v109
	v_mad_u64_u32 v[102:103], s[18:19], v41, s23, v[100:101]
	v_lshlrev_b32_e32 v42, 4, v108
	v_add_u32_e32 v42, 0x1400, v42
	v_add_co_u32_e32 v102, vcc, v102, v42
	s_nop 1
	v_addc_co_u32_e32 v103, vcc, 0, v103, vcc
	global_load_dwordx4 v[12:15], v[102:103], off
	s_and_b64 vcc, exec, s[42:43]
	s_cbranch_vccz .Ldft_st_ctx
	v_lshrrev_b32_e32 v109, 5, v44
	v_add_u32_e32 v42, s64, v109
	v_add_u32_e32 v42, 0xffffff00, v42
	v_sub_u32_e32 v43, 0x800, v42
	v_cmp_ne_u32_e32 vcc, 0, v42
	s_nop 1
	v_cndmask_b32_e32 v43, v242, v43, vcc
	v_add_u32_e32 v43, s7, v43
	v_mad_u64_u32 v[104:105], s[18:19], v43, s23, v[100:101]
	v_lshlrev_b32_e32 v42, 4, v108
	v_add_u32_e32 v42, 0x1400, v42
	v_add_co_u32_e32 v104, vcc, v104, v42
	s_nop 1
	v_addc_co_u32_e32 v105, vcc, 0, v105, vcc
	global_load_dwordx4 v[16:19], v[104:105], off
	v_lshrrev_b32_e32 v109, 5, v44
	v_add_u32_e32 v109, 16, v109
	v_add_u32_e32 v42, s64, v109
	v_add_u32_e32 v42, 0xffffff00, v42
	v_sub_u32_e32 v43, 0x800, v42
	v_cmp_ne_u32_e32 vcc, 0, v42
	s_nop 1
	v_cndmask_b32_e32 v43, v242, v43, vcc
	v_add_u32_e32 v43, s7, v43
	v_mad_u64_u32 v[104:105], s[18:19], v43, s23, v[100:101]
	v_lshlrev_b32_e32 v42, 4, v108
	v_add_u32_e32 v42, 0x1400, v42
	v_add_co_u32_e32 v104, vcc, v104, v42
	s_nop 1
	v_addc_co_u32_e32 v105, vcc, 0, v105, vcc
	global_load_dwordx4 v[20:23], v[104:105], off
	v_lshrrev_b32_e32 v109, 5, v44
	v_add_u32_e32 v109, 32, v109
	v_add_u32_e32 v42, s64, v109
	v_add_u32_e32 v42, 0xffffff00, v42
	v_sub_u32_e32 v43, 0x800, v42
	v_cmp_ne_u32_e32 vcc, 0, v42
	s_nop 1
	v_cndmask_b32_e32 v43, v242, v43, vcc
	v_add_u32_e32 v43, s7, v43
	v_mad_u64_u32 v[104:105], s[18:19], v43, s23, v[100:101]
	v_lshlrev_b32_e32 v42, 4, v108
	v_add_u32_e32 v42, 0x1400, v42
	v_add_co_u32_e32 v104, vcc, v104, v42
	s_nop 1
	v_addc_co_u32_e32 v105, vcc, 0, v105, vcc
	global_load_dwordx4 v[24:27], v[104:105], off
	v_lshrrev_b32_e32 v109, 5, v44
	v_add_u32_e32 v109, 48, v109
	v_add_u32_e32 v42, s64, v109
	v_add_u32_e32 v42, 0xffffff00, v42
	v_sub_u32_e32 v43, 0x800, v42
	v_cmp_ne_u32_e32 vcc, 0, v42
	s_nop 1
	v_cndmask_b32_e32 v43, v242, v43, vcc
	v_add_u32_e32 v43, s7, v43
	v_mad_u64_u32 v[104:105], s[18:19], v43, s23, v[100:101]
	v_lshlrev_b32_e32 v42, 4, v108
	v_add_u32_e32 v42, 0x1400, v42
	v_add_co_u32_e32 v104, vcc, v104, v42
	s_nop 1
	v_addc_co_u32_e32 v105, vcc, 0, v105, vcc
	global_load_dwordx4 v[28:31], v[104:105], off
.Ldft_st_ctx:
	v_mul_u32_u24_e32 v120, v33, v34
	v_lshlrev_b32_e32 v122, 1, v34
	v_and_b32_e32 v41, 63, v120
	v_cvt_f32_u32_e32 v41, v41
	v_mul_f32_e32 v41, 0x3c800000, v41
	v_cos_f32_e32 v42, v41
	v_sin_f32_e32 v43, v41
	v_add_u32_e32 v120, v120, v122
	v_mul_f32_e32 v130, 0x3e000000, v42
	v_mul_f32_e32 v194, 0x3e000000, v43
	v_and_b32_e32 v41, 63, v120
	v_cvt_f32_u32_e32 v41, v41
	v_mul_f32_e32 v41, 0x3c800000, v41
	v_cos_f32_e32 v42, v41
	v_sin_f32_e32 v43, v41
	v_add_u32_e32 v120, v120, v122
	v_mul_f32_e32 v131, 0x3e000000, v42
	v_mul_f32_e32 v195, 0x3e000000, v43
	v_and_b32_e32 v41, 63, v120
	v_cvt_f32_u32_e32 v41, v41
	v_mul_f32_e32 v41, 0x3c800000, v41
	v_cos_f32_e32 v42, v41
	v_sin_f32_e32 v43, v41
	v_add_u32_e32 v120, v120, v122
	v_mul_f32_e32 v132, 0x3e000000, v42
	v_mul_f32_e32 v196, 0x3e000000, v43
	v_and_b32_e32 v41, 63, v120
	v_cvt_f32_u32_e32 v41, v41
	v_mul_f32_e32 v41, 0x3c800000, v41
	v_cos_f32_e32 v42, v41
	v_sin_f32_e32 v43, v41
	v_add_u32_e32 v120, v120, v122
	v_mul_f32_e32 v133, 0x3e000000, v42
	v_mul_f32_e32 v197, 0x3e000000, v43
	v_and_b32_e32 v41, 63, v120
	v_cvt_f32_u32_e32 v41, v41
	v_mul_f32_e32 v41, 0x3c800000, v41
	v_cos_f32_e32 v42, v41
	v_sin_f32_e32 v43, v41
	v_add_u32_e32 v120, v120, v122
	v_mul_f32_e32 v134, 0x3e000000, v42
	v_mul_f32_e32 v198, 0x3e000000, v43
	v_and_b32_e32 v41, 63, v120
	v_cvt_f32_u32_e32 v41, v41
	v_mul_f32_e32 v41, 0x3c800000, v41
	v_cos_f32_e32 v42, v41
	v_sin_f32_e32 v43, v41
	v_add_u32_e32 v120, v120, v122
	v_mul_f32_e32 v135, 0x3e000000, v42
	v_mul_f32_e32 v199, 0x3e000000, v43
	v_and_b32_e32 v41, 63, v120
	v_cvt_f32_u32_e32 v41, v41
; __device__ __forceinline__ void phase_prep(const Params& P, int l, unsigned char* lds) {
;     ...
;             for (int rep = 0; rep < 4; ++rep) {
;                 const int id = tid + 512 * rep, tok = id >> 5, ch = id & 31;
;                 const u32x4 w = *(const u32x4*)(proj + (size_t)(r0 + tok) * INW + PD_U + 8 * ch);
;                 f32x4 a0 = (f32x4){bflo(w.x), bfhi(w.x), bflo(w.y), bfhi(w.y)}, a1 = (f32x4){bflo(w.z), bfhi(w.z), bflo(w.w), bfhi(w.w)};
;                 float* d = U + tok * 256 + 8 * ch;
;                 if (!is_ctx) {
;                     const int tg = t0 - CTX + tok, mt = (tg == 0) ? SEQ / 2 : SEQ - tg;
;                     const u32x4 m = *(const u32x4*)(proj + ((size_t)b * TT + CTX + mt) * INW + PD_U + 8 * ch);
;                     const f32x4 m0 = (f32x4){bflo(m.x), bfhi(m.x), bflo(m.y), bfhi(m.y)}, m1 = (f32x4){bflo(m.z), bfhi(m.z), bflo(m.w), bfhi(m.w)};
;                     float* d2 = U2 + tok * 256 + 8 * ch;
;                     if (tg == 0) { *(f32x4*)d2 = m0; *(f32x4*)(d2 + 4) = m1; }
;                     else { *(f32x4*)d2 = a0 - m0; *(f32x4*)(d2 + 4) = a1 - m1; a0 = a0 + m0; a1 = a1 + m1; }
;                 }
;                 *(f32x4*)d = a0; *(f32x4*)(d + 4) = a1;
;     ...
;                 for (int q = 0; q < 4; ++q) { const float rev = (float)((c * (cp0 + q)) & 63) * (1.0f / 64.0f); cv[q] = __builtin_amdgcn_cosf(rev) * 0.125f; sv[q] = __builtin_amdgcn_sinf(rev) * 0.125f; }
	v_mul_f32_e32 v41, 0x3c800000, v41
	v_cos_f32_e32 v42, v41
	v_sin_f32_e32 v43, v41
	v_add_u32_e32 v120, v120, v122
	v_mul_f32_e32 v136, 0x3e000000, v42
	v_mul_f32_e32 v204, 0x3e000000, v43
	v_and_b32_e32 v41, 63, v120
	v_cvt_f32_u32_e32 v41, v41
	v_mul_f32_e32 v41, 0x3c800000, v41
	v_cos_f32_e32 v42, v41
	v_sin_f32_e32 v43, v41
	v_add_u32_e32 v120, v120, v122
	v_mul_f32_e32 v137, 0x3e000000, v42
	v_mul_f32_e32 v205, 0x3e000000, v43
	v_and_b32_e32 v41, 63, v120
	v_cvt_f32_u32_e32 v41, v41
	v_mul_f32_e32 v41, 0x3c800000, v41
	v_cos_f32_e32 v42, v41
	v_sin_f32_e32 v43, v41
	v_add_u32_e32 v120, v120, v122
	v_mul_f32_e32 v138, 0x3e000000, v42
	v_mul_f32_e32 v206, 0x3e000000, v43
	v_and_b32_e32 v41, 63, v120
	v_cvt_f32_u32_e32 v41, v41
	v_mul_f32_e32 v41, 0x3c800000, v41
	v_cos_f32_e32 v42, v41
	v_sin_f32_e32 v43, v41
	v_add_u32_e32 v120, v120, v122
	v_mul_f32_e32 v139, 0x3e000000, v42
	v_mul_f32_e32 v207, 0x3e000000, v43
	v_and_b32_e32 v41, 63, v120
	v_cvt_f32_u32_e32 v41, v41
	v_mul_f32_e32 v41, 0x3c800000, v41
	v_cos_f32_e32 v42, v41
	v_sin_f32_e32 v43, v41
	v_add_u32_e32 v120, v120, v122
	v_mul_f32_e32 v140, 0x3e000000, v42
	v_mul_f32_e32 v208, 0x3e000000, v43
	v_and_b32_e32 v41, 63, v120
	v_cvt_f32_u32_e32 v41, v41
	v_mul_f32_e32 v41, 0x3c800000, v41
	v_cos_f32_e32 v42, v41
	v_sin_f32_e32 v43, v41
	v_add_u32_e32 v120, v120, v122
	v_mul_f32_e32 v141, 0x3e000000, v42
	v_mul_f32_e32 v209, 0x3e000000, v43
	v_and_b32_e32 v41, 63, v120
	v_cvt_f32_u32_e32 v41, v41
	v_mul_f32_e32 v41, 0x3c800000, v41
	v_cos_f32_e32 v42, v41
	v_sin_f32_e32 v43, v41
	v_add_u32_e32 v120, v120, v122
	v_mul_f32_e32 v142, 0x3e000000, v42
	v_mul_f32_e32 v210, 0x3e000000, v43
	v_and_b32_e32 v41, 63, v120
	v_cvt_f32_u32_e32 v41, v41
	v_mul_f32_e32 v41, 0x3c800000, v41
	v_cos_f32_e32 v42, v41
	v_sin_f32_e32 v43, v41
	v_add_u32_e32 v120, v120, v122
	v_mul_f32_e32 v143, 0x3e000000, v42
	v_mul_f32_e32 v211, 0x3e000000, v43
	v_and_b32_e32 v41, 63, v120
	v_cvt_f32_u32_e32 v41, v41
	v_mul_f32_e32 v41, 0x3c800000, v41
	v_cos_f32_e32 v42, v41
	v_sin_f32_e32 v43, v41
	v_add_u32_e32 v120, v120, v122
	v_mul_f32_e32 v144, 0x3e000000, v42
	v_mul_f32_e32 v212, 0x3e000000, v43
	v_and_b32_e32 v41, 63, v120
	v_cvt_f32_u32_e32 v41, v41
	v_mul_f32_e32 v41, 0x3c800000, v41
	v_cos_f32_e32 v42, v41
	v_sin_f32_e32 v43, v41
	v_add_u32_e32 v120, v120, v122
	v_mul_f32_e32 v145, 0x3e000000, v42
	v_mul_f32_e32 v213, 0x3e000000, v43
	v_and_b32_e32 v41, 63, v120
	v_cvt_f32_u32_e32 v41, v41
	v_mul_f32_e32 v41, 0x3c800000, v41
	v_cos_f32_e32 v42, v41
	v_sin_f32_e32 v43, v41
	v_add_u32_e32 v120, v120, v122
	v_mul_f32_e32 v146, 0x3e000000, v42
	v_mul_f32_e32 v214, 0x3e000000, v43
	v_and_b32_e32 v41, 63, v120
	v_cvt_f32_u32_e32 v41, v41
	v_mul_f32_e32 v41, 0x3c800000, v41
	v_cos_f32_e32 v42, v41
	v_sin_f32_e32 v43, v41
	v_add_u32_e32 v120, v120, v122
	v_mul_f32_e32 v147, 0x3e000000, v42
	v_mul_f32_e32 v215, 0x3e000000, v43
	v_and_b32_e32 v41, 63, v120
	v_cvt_f32_u32_e32 v41, v41
	v_mul_f32_e32 v41, 0x3c800000, v41
	v_cos_f32_e32 v42, v41
	v_sin_f32_e32 v43, v41
	v_add_u32_e32 v120, v120, v122
	v_mul_f32_e32 v148, 0x3e000000, v42
	v_mul_f32_e32 v216, 0x3e000000, v43
	v_and_b32_e32 v41, 63, v120
	v_cvt_f32_u32_e32 v41, v41
	v_mul_f32_e32 v41, 0x3c800000, v41
	v_cos_f32_e32 v42, v41
	v_sin_f32_e32 v43, v41
	v_add_u32_e32 v120, v120, v122
	v_mul_f32_e32 v149, 0x3e000000, v42
	v_mul_f32_e32 v217, 0x3e000000, v43
	v_and_b32_e32 v41, 63, v120
	v_cvt_f32_u32_e32 v41, v41
	v_mul_f32_e32 v41, 0x3c800000, v41
	v_cos_f32_e32 v42, v41
	v_sin_f32_e32 v43, v41
	v_add_u32_e32 v120, v120, v122
	v_mul_f32_e32 v150, 0x3e000000, v42
	v_mul_f32_e32 v218, 0x3e000000, v43
	v_and_b32_e32 v41, 63, v120
	v_cvt_f32_u32_e32 v41, v41
	v_mul_f32_e32 v41, 0x3c800000, v41
	v_cos_f32_e32 v42, v41
	v_sin_f32_e32 v43, v41
	v_add_u32_e32 v120, v120, v122
	v_mul_f32_e32 v151, 0x3e000000, v42
	v_mul_f32_e32 v219, 0x3e000000, v43
	v_and_b32_e32 v41, 63, v120
	v_cvt_f32_u32_e32 v41, v41
	v_mul_f32_e32 v41, 0x3c800000, v41
	v_cos_f32_e32 v42, v41
	v_sin_f32_e32 v43, v41
	v_add_u32_e32 v120, v120, v122
	v_mul_f32_e32 v152, 0x3e000000, v42
	v_mul_f32_e32 v220, 0x3e000000, v43
	v_and_b32_e32 v41, 63, v120
	v_cvt_f32_u32_e32 v41, v41
	v_mul_f32_e32 v41, 0x3c800000, v41
	v_cos_f32_e32 v42, v41
	v_sin_f32_e32 v43, v41
	v_add_u32_e32 v120, v120, v122
	v_mul_f32_e32 v153, 0x3e000000, v42
	v_mul_f32_e32 v221, 0x3e000000, v43
	v_and_b32_e32 v41, 63, v120
	v_cvt_f32_u32_e32 v41, v41
	v_mul_f32_e32 v41, 0x3c800000, v41
	v_cos_f32_e32 v42, v41
	v_sin_f32_e32 v43, v41
	v_add_u32_e32 v120, v120, v122
	v_mul_f32_e32 v154, 0x3e000000, v42
	v_mul_f32_e32 v222, 0x3e000000, v43
	v_and_b32_e32 v41, 63, v120
	v_cvt_f32_u32_e32 v41, v41
	v_mul_f32_e32 v41, 0x3c800000, v41
	v_cos_f32_e32 v42, v41
	v_sin_f32_e32 v43, v41
	v_add_u32_e32 v120, v120, v122
	v_mul_f32_e32 v155, 0x3e000000, v42
	v_mul_f32_e32 v223, 0x3e000000, v43
	v_and_b32_e32 v41, 63, v120
	v_cvt_f32_u32_e32 v41, v41
	v_mul_f32_e32 v41, 0x3c800000, v41
	v_cos_f32_e32 v42, v41
	v_sin_f32_e32 v43, v41
	v_add_u32_e32 v120, v120, v122
	v_mul_f32_e32 v156, 0x3e000000, v42
	v_mul_f32_e32 v224, 0x3e000000, v43
	v_and_b32_e32 v41, 63, v120
	v_cvt_f32_u32_e32 v41, v41
	v_mul_f32_e32 v41, 0x3c800000, v41
	v_cos_f32_e32 v42, v41
	v_sin_f32_e32 v43, v41
	v_add_u32_e32 v120, v120, v122
	v_mul_f32_e32 v157, 0x3e000000, v42
	v_mul_f32_e32 v225, 0x3e000000, v43
	v_and_b32_e32 v41, 63, v120
	v_cvt_f32_u32_e32 v41, v41
	v_mul_f32_e32 v41, 0x3c800000, v41
	v_cos_f32_e32 v42, v41
	v_sin_f32_e32 v43, v41
	v_add_u32_e32 v120, v120, v122
	v_mul_f32_e32 v158, 0x3e000000, v42
	v_mul_f32_e32 v226, 0x3e000000, v43
	v_and_b32_e32 v41, 63, v120
	v_cvt_f32_u32_e32 v41, v41
	v_mul_f32_e32 v41, 0x3c800000, v41
	v_cos_f32_e32 v42, v41
	v_sin_f32_e32 v43, v41
	v_add_u32_e32 v120, v120, v122
	v_mul_f32_e32 v159, 0x3e000000, v42
	v_mul_f32_e32 v227, 0x3e000000, v43
	v_and_b32_e32 v41, 63, v120
	v_cvt_f32_u32_e32 v41, v41
	v_mul_f32_e32 v41, 0x3c800000, v41
	v_cos_f32_e32 v42, v41
	v_sin_f32_e32 v43, v41
	v_add_u32_e32 v120, v120, v122
	v_mul_f32_e32 v160, 0x3e000000, v42
	v_mul_f32_e32 v228, 0x3e000000, v43
	v_and_b32_e32 v41, 63, v120
	v_cvt_f32_u32_e32 v41, v41
	v_mul_f32_e32 v41, 0x3c800000, v41
	v_cos_f32_e32 v42, v41
	v_sin_f32_e32 v43, v41
	v_add_u32_e32 v120, v120, v122
	v_mul_f32_e32 v161, 0x3e000000, v42
	v_mul_f32_e32 v229, 0x3e000000, v43
	s_waitcnt vmcnt(0)
	v_lshrrev_b32_e32 v109, 5, v44
	v_and_b32_e32 v41, 31, v109
	v_lshlrev_b32_e32 v42, 1, v108
	v_xor_b32_e32 v41, v42, v41
	v_lshlrev_b32_e32 v62, 10, v109
	v_lshl_add_u32 v62, v41, 4, v62
	v_xor_b32_e32 v63, 16, v62
	v_lshlrev_b32_e32 v46, 16, v0
	v_and_b32_e32 v47, 0xffff0000, v0
	v_lshlrev_b32_e32 v48, 16, v1
	v_and_b32_e32 v49, 0xffff0000, v1
	v_lshlrev_b32_e32 v50, 16, v2
	v_and_b32_e32 v51, 0xffff0000, v2
	v_lshlrev_b32_e32 v52, 16, v3
	v_and_b32_e32 v53, 0xffff0000, v3
	s_and_b64 vcc, exec, s[42:43]
	s_cbranch_vccz .Ldft_wr_u0
; __device__ __forceinline__ void phase_prep(const Params& P, int l, unsigned char* lds) {
;     ...
;             for (int rep = 0; rep < 4; ++rep) {
;                 const int id = tid + 512 * rep, tok = id >> 5, ch = id & 31;
;                 const u32x4 w = *(const u32x4*)(proj + (size_t)(r0 + tok) * INW + PD_U + 8 * ch);
;                 f32x4 a0 = (f32x4){bflo(w.x), bfhi(w.x), bflo(w.y), bfhi(w.y)}, a1 = (f32x4){bflo(w.z), bfhi(w.z), bflo(w.w), bfhi(w.w)};
;                 float* d = U + tok * 256 + 8 * ch;
;                 if (!is_ctx) {
;                     const int tg = t0 - CTX + tok, mt = (tg == 0) ? SEQ / 2 : SEQ - tg;
;                     const u32x4 m = *(const u32x4*)(proj + ((size_t)b * TT + CTX + mt) * INW + PD_U + 8 * ch);
;                     const f32x4 m0 = (f32x4){bflo(m.x), bfhi(m.x), bflo(m.y), bfhi(m.y)}, m1 = (f32x4){bflo(m.z), bfhi(m.z), bflo(m.w), bfhi(m.w)};
;                     float* d2 = U2 + tok * 256 + 8 * ch;
;                     if (tg == 0) { *(f32x4*)d2 = m0; *(f32x4*)(d2 + 4) = m1; }
;                     else { *(f32x4*)d2 = a0 - m0; *(f32x4*)(d2 + 4) = a1 - m1; a0 = a0 + m0; a1 = a1 + m1; }
;                 }
;                 *(f32x4*)d = a0; *(f32x4*)(d + 4) = a1;
;             }
;             __syncthreads();
	v_lshlrev_b32_e32 v54, 16, v16
	v_and_b32_e32 v55, 0xffff0000, v16
	v_lshlrev_b32_e32 v56, 16, v17
	v_and_b32_e32 v57, 0xffff0000, v17
	v_lshlrev_b32_e32 v58, 16, v18
	v_and_b32_e32 v59, 0xffff0000, v18
	v_lshlrev_b32_e32 v60, 16, v19
	v_and_b32_e32 v61, 0xffff0000, v19
	v_add_u32_e32 v42, s64, v109
	v_mov_b32_e32 v43, 0x100
	v_cmp_ne_u32_e64 s[50:51], v43, v42
	s_nop 1
	v_sub_f32_e32 v43, v46, v54
	v_add_f32_e32 v126, v46, v54
	v_cndmask_b32_e64 v54, v54, v43, s[50:51]
	v_cndmask_b32_e64 v46, v46, v126, s[50:51]
	v_sub_f32_e32 v43, v47, v55
	v_add_f32_e32 v126, v47, v55
	v_cndmask_b32_e64 v55, v55, v43, s[50:51]
	v_cndmask_b32_e64 v47, v47, v126, s[50:51]
	v_sub_f32_e32 v43, v48, v56
	v_add_f32_e32 v126, v48, v56
	v_cndmask_b32_e64 v56, v56, v43, s[50:51]
	v_cndmask_b32_e64 v48, v48, v126, s[50:51]
	v_sub_f32_e32 v43, v49, v57
	v_add_f32_e32 v126, v49, v57
	v_cndmask_b32_e64 v57, v57, v43, s[50:51]
	v_cndmask_b32_e64 v49, v49, v126, s[50:51]
	v_sub_f32_e32 v43, v50, v58
	v_add_f32_e32 v126, v50, v58
	v_cndmask_b32_e64 v58, v58, v43, s[50:51]
	v_cndmask_b32_e64 v50, v50, v126, s[50:51]
	v_sub_f32_e32 v43, v51, v59
	v_add_f32_e32 v126, v51, v59
	v_cndmask_b32_e64 v59, v59, v43, s[50:51]
	v_cndmask_b32_e64 v51, v51, v126, s[50:51]
	v_sub_f32_e32 v43, v52, v60
	v_add_f32_e32 v126, v52, v60
	v_cndmask_b32_e64 v60, v60, v43, s[50:51]
	v_cndmask_b32_e64 v52, v52, v126, s[50:51]
	v_sub_f32_e32 v43, v53, v61
	v_add_f32_e32 v126, v53, v61
	v_cndmask_b32_e64 v61, v61, v43, s[50:51]
	v_cndmask_b32_e64 v53, v53, v126, s[50:51]
	v_add_u32_e32 v42, 0x10000, v62
	v_add_u32_e32 v43, 0x10000, v63
	ds_write_b128 v42, v[54:57]
	ds_write_b128 v43, v[58:61]
.Ldft_wr_u0:
	ds_write_b128 v62, v[46:49]
	ds_write_b128 v63, v[50:53]
	v_lshrrev_b32_e32 v109, 5, v44
	v_add_u32_e32 v109, 16, v109
	v_and_b32_e32 v41, 31, v109
	v_lshlrev_b32_e32 v42, 1, v108
	v_xor_b32_e32 v41, v42, v41
	v_lshlrev_b32_e32 v62, 10, v109
	v_lshl_add_u32 v62, v41, 4, v62
	v_xor_b32_e32 v63, 16, v62
	v_lshlrev_b32_e32 v46, 16, v4
	v_and_b32_e32 v47, 0xffff0000, v4
	v_lshlrev_b32_e32 v48, 16, v5
	v_and_b32_e32 v49, 0xffff0000, v5
	v_lshlrev_b32_e32 v50, 16, v6
	v_and_b32_e32 v51, 0xffff0000, v6
	v_lshlrev_b32_e32 v52, 16, v7
	v_and_b32_e32 v53, 0xffff0000, v7
	s_and_b64 vcc, exec, s[42:43]
	s_cbranch_vccz .Ldft_wr_u1
	v_lshlrev_b32_e32 v54, 16, v20
	v_and_b32_e32 v55, 0xffff0000, v20
	v_lshlrev_b32_e32 v56, 16, v21
	v_and_b32_e32 v57, 0xffff0000, v21
	v_lshlrev_b32_e32 v58, 16, v22
	v_and_b32_e32 v59, 0xffff0000, v22
	v_lshlrev_b32_e32 v60, 16, v23
	v_and_b32_e32 v61, 0xffff0000, v23
	v_add_u32_e32 v42, s64, v109
	v_mov_b32_e32 v43, 0x100
	v_cmp_ne_u32_e64 s[50:51], v43, v42
	s_nop 1
	v_sub_f32_e32 v43, v46, v54
	v_add_f32_e32 v126, v46, v54
	v_cndmask_b32_e64 v54, v54, v43, s[50:51]
	v_cndmask_b32_e64 v46, v46, v126, s[50:51]
	v_sub_f32_e32 v43, v47, v55
	v_add_f32_e32 v126, v47, v55
	v_cndmask_b32_e64 v55, v55, v43, s[50:51]
	v_cndmask_b32_e64 v47, v47, v126, s[50:51]
	v_sub_f32_e32 v43, v48, v56
	v_add_f32_e32 v126, v48, v56
	v_cndmask_b32_e64 v56, v56, v43, s[50:51]
	v_cndmask_b32_e64 v48, v48, v126, s[50:51]
	v_sub_f32_e32 v43, v49, v57
	v_add_f32_e32 v126, v49, v57
	v_cndmask_b32_e64 v57, v57, v43, s[50:51]
	v_cndmask_b32_e64 v49, v49, v126, s[50:51]
	v_sub_f32_e32 v43, v50, v58
	v_add_f32_e32 v126, v50, v58
	v_cndmask_b32_e64 v58, v58, v43, s[50:51]
	v_cndmask_b32_e64 v50, v50, v126, s[50:51]
	v_sub_f32_e32 v43, v51, v59
	v_add_f32_e32 v126, v51, v59
	v_cndmask_b32_e64 v59, v59, v43, s[50:51]
	v_cndmask_b32_e64 v51, v51, v126, s[50:51]
	v_sub_f32_e32 v43, v52, v60
	v_add_f32_e32 v126, v52, v60
	v_cndmask_b32_e64 v60, v60, v43, s[50:51]
	v_cndmask_b32_e64 v52, v52, v126, s[50:51]
	v_sub_f32_e32 v43, v53, v61
	v_add_f32_e32 v126, v53, v61
	v_cndmask_b32_e64 v61, v61, v43, s[50:51]
	v_cndmask_b32_e64 v53, v53, v126, s[50:51]
	v_add_u32_e32 v42, 0x10000, v62
	v_add_u32_e32 v43, 0x10000, v63
	ds_write_b128 v42, v[54:57]
	ds_write_b128 v43, v[58:61]
.Ldft_wr_u1:
	ds_write_b128 v62, v[46:49]
	ds_write_b128 v63, v[50:53]
	v_lshrrev_b32_e32 v109, 5, v44
	v_add_u32_e32 v109, 32, v109
	v_and_b32_e32 v41, 31, v109
	v_lshlrev_b32_e32 v42, 1, v108
	v_xor_b32_e32 v41, v42, v41
	v_lshlrev_b32_e32 v62, 10, v109
	v_lshl_add_u32 v62, v41, 4, v62
	v_xor_b32_e32 v63, 16, v62
	v_lshlrev_b32_e32 v46, 16, v8
	v_and_b32_e32 v47, 0xffff0000, v8
	v_lshlrev_b32_e32 v48, 16, v9
	v_and_b32_e32 v49, 0xffff0000, v9
	v_lshlrev_b32_e32 v50, 16, v10
	v_and_b32_e32 v51, 0xffff0000, v10
	v_lshlrev_b32_e32 v52, 16, v11
	v_and_b32_e32 v53, 0xffff0000, v11
	s_and_b64 vcc, exec, s[42:43]
	s_cbranch_vccz .Ldft_wr_u2
	v_lshlrev_b32_e32 v54, 16, v24
	v_and_b32_e32 v55, 0xffff0000, v24
	v_lshlrev_b32_e32 v56, 16, v25
	v_and_b32_e32 v57, 0xffff0000, v25
	v_lshlrev_b32_e32 v58, 16, v26
	v_and_b32_e32 v59, 0xffff0000, v26
	v_lshlrev_b32_e32 v60, 16, v27
	v_and_b32_e32 v61, 0xffff0000, v27
	v_add_u32_e32 v42, s64, v109
	v_mov_b32_e32 v43, 0x100
	v_cmp_ne_u32_e64 s[50:51], v43, v42
	s_nop 1
	v_sub_f32_e32 v43, v46, v54
	v_add_f32_e32 v126, v46, v54
	v_cndmask_b32_e64 v54, v54, v43, s[50:51]
	v_cndmask_b32_e64 v46, v46, v126, s[50:51]
	v_sub_f32_e32 v43, v47, v55
	v_add_f32_e32 v126, v47, v55
	v_cndmask_b32_e64 v55, v55, v43, s[50:51]
	v_cndmask_b32_e64 v47, v47, v126, s[50:51]
	v_sub_f32_e32 v43, v48, v56
	v_add_f32_e32 v126, v48, v56
	v_cndmask_b32_e64 v56, v56, v43, s[50:51]
	v_cndmask_b32_e64 v48, v48, v126, s[50:51]
	v_sub_f32_e32 v43, v49, v57
	v_add_f32_e32 v126, v49, v57
	v_cndmask_b32_e64 v57, v57, v43, s[50:51]
	v_cndmask_b32_e64 v49, v49, v126, s[50:51]
	v_sub_f32_e32 v43, v50, v58
	v_add_f32_e32 v126, v50, v58
	v_cndmask_b32_e64 v58, v58, v43, s[50:51]
	v_cndmask_b32_e64 v50, v50, v126, s[50:51]
	v_sub_f32_e32 v43, v51, v59
	v_add_f32_e32 v126, v51, v59
	v_cndmask_b32_e64 v59, v59, v43, s[50:51]
	v_cndmask_b32_e64 v51, v51, v126, s[50:51]
	v_sub_f32_e32 v43, v52, v60
	v_add_f32_e32 v126, v52, v60
	v_cndmask_b32_e64 v60, v60, v43, s[50:51]
	v_cndmask_b32_e64 v52, v52, v126, s[50:51]
	v_sub_f32_e32 v43, v53, v61
	v_add_f32_e32 v126, v53, v61
	v_cndmask_b32_e64 v61, v61, v43, s[50:51]
	v_cndmask_b32_e64 v53, v53, v126, s[50:51]
	v_add_u32_e32 v42, 0x10000, v62
	v_add_u32_e32 v43, 0x10000, v63
	ds_write_b128 v42, v[54:57]
	ds_write_b128 v43, v[58:61]
; __device__ __forceinline__ void phase_prep(const Params& P, int l, unsigned char* lds) {
;     ...
;             __syncthreads();
;             const int n0 = (tid & 63) * 4, t8 = (tid >> 6) * 8, cp0 = n0 & 63, g = n0 >> 6;
;             const bool sp0 = (!is_ctx) && (t0 == CTX) && (t8 == 0);
;             float aC[4][8], aS[4][8];
; #pragma unroll
;             for (int q = 0; q < 4; ++q)
; #pragma unroll
;                 for (int t = 0; t < 8; ++t) { aC[q][t] = 0.f; aS[q][t] = 0.f; }
;             const float* ub = U + t8 * 256 + g * 64;
;             const float* ub2 = is_ctx ? ub : ub + 64 * 256;
; #pragma unroll 2
;             for (int c = 0; c < 64; ++c) {
;                 float cv[4], sv[4];
; #pragma unroll
;                 for (int q = 0; q < 4; ++q) { const float rev = (float)((c * (cp0 + q)) & 63) * (1.0f / 64.0f); cv[q] = __builtin_amdgcn_cosf(rev) * 0.125f; sv[q] = __builtin_amdgcn_sinf(rev) * 0.125f; }
; #pragma unroll
;                 for (int t = 0; t < 8; ++t) { const float u = ub[t * 256 + c], u2 = ub2[t * 256 + c];
; #pragma unroll
;                     for (int q = 0; q < 4; ++q) { aC[q][t] += u * cv[q]; aS[q][t] += u2 * ((t == 0 && sp0) ? cv[q] : sv[q]); } }
;             }
.Ldft_wr_u2:
	ds_write_b128 v62, v[46:49]
	ds_write_b128 v63, v[50:53]
	v_lshrrev_b32_e32 v109, 5, v44
	v_add_u32_e32 v109, 48, v109
	v_and_b32_e32 v41, 31, v109
	v_lshlrev_b32_e32 v42, 1, v108
	v_xor_b32_e32 v41, v42, v41
	v_lshlrev_b32_e32 v62, 10, v109
	v_lshl_add_u32 v62, v41, 4, v62
	v_xor_b32_e32 v63, 16, v62
	v_lshlrev_b32_e32 v46, 16, v12
	v_and_b32_e32 v47, 0xffff0000, v12
	v_lshlrev_b32_e32 v48, 16, v13
	v_and_b32_e32 v49, 0xffff0000, v13
	v_lshlrev_b32_e32 v50, 16, v14
	v_and_b32_e32 v51, 0xffff0000, v14
	v_lshlrev_b32_e32 v52, 16, v15
	v_and_b32_e32 v53, 0xffff0000, v15
	s_and_b64 vcc, exec, s[42:43]
	s_cbranch_vccz .Ldft_wr_u3
	v_lshlrev_b32_e32 v54, 16, v28
	v_and_b32_e32 v55, 0xffff0000, v28
	v_lshlrev_b32_e32 v56, 16, v29
	v_and_b32_e32 v57, 0xffff0000, v29
	v_lshlrev_b32_e32 v58, 16, v30
	v_and_b32_e32 v59, 0xffff0000, v30
	v_lshlrev_b32_e32 v60, 16, v31
	v_and_b32_e32 v61, 0xffff0000, v31
	v_add_u32_e32 v42, s64, v109
	v_mov_b32_e32 v43, 0x100
	v_cmp_ne_u32_e64 s[50:51], v43, v42
	s_nop 1
	v_sub_f32_e32 v43, v46, v54
	v_add_f32_e32 v126, v46, v54
	v_cndmask_b32_e64 v54, v54, v43, s[50:51]
	v_cndmask_b32_e64 v46, v46, v126, s[50:51]
	v_sub_f32_e32 v43, v47, v55
	v_add_f32_e32 v126, v47, v55
	v_cndmask_b32_e64 v55, v55, v43, s[50:51]
	v_cndmask_b32_e64 v47, v47, v126, s[50:51]
	v_sub_f32_e32 v43, v48, v56
	v_add_f32_e32 v126, v48, v56
	v_cndmask_b32_e64 v56, v56, v43, s[50:51]
	v_cndmask_b32_e64 v48, v48, v126, s[50:51]
	v_sub_f32_e32 v43, v49, v57
	v_add_f32_e32 v126, v49, v57
	v_cndmask_b32_e64 v57, v57, v43, s[50:51]
	v_cndmask_b32_e64 v49, v49, v126, s[50:51]
	v_sub_f32_e32 v43, v50, v58
	v_add_f32_e32 v126, v50, v58
	v_cndmask_b32_e64 v58, v58, v43, s[50:51]
	v_cndmask_b32_e64 v50, v50, v126, s[50:51]
	v_sub_f32_e32 v43, v51, v59
	v_add_f32_e32 v126, v51, v59
	v_cndmask_b32_e64 v59, v59, v43, s[50:51]
	v_cndmask_b32_e64 v51, v51, v126, s[50:51]
	v_sub_f32_e32 v43, v52, v60
	v_add_f32_e32 v126, v52, v60
	v_cndmask_b32_e64 v60, v60, v43, s[50:51]
	v_cndmask_b32_e64 v52, v52, v126, s[50:51]
	v_sub_f32_e32 v43, v53, v61
	v_add_f32_e32 v126, v53, v61
	v_cndmask_b32_e64 v61, v61, v43, s[50:51]
	v_cndmask_b32_e64 v53, v53, v126, s[50:51]
	v_add_u32_e32 v42, 0x10000, v62
	v_add_u32_e32 v43, 0x10000, v63
	ds_write_b128 v42, v[54:57]
	ds_write_b128 v43, v[58:61]
.Ldft_wr_u3:
	ds_write_b128 v62, v[46:49]
	ds_write_b128 v63, v[50:53]
	s_waitcnt lgkmcnt(0)
	s_barrier
	s_lshl_b32 s7, s13, 15
	v_lshl_add_u32 v94, v34, 10, s7
	v_lshl_add_u32 v94, v33, 2, v94
	s_lshl_b32 s18, s15, 4
	s_mov_b32 s12, 0x10000
	s_and_b64 vcc, exec, s[42:43]
	s_cselect_b32 s12, s12, 0
	v_xor_b32_e32 v103, s18, v34
	v_xor_b32_e32 v95, 0, v103
	v_lshl_add_u32 v95, v95, 4, v94
	v_add_u32_e32 v96, s12, v95
	ds_read_b32 v37, v95
	ds_read_b32 v38, v95 offset:8
	ds_read_b32 v39, v96
	ds_read_b32 v40, v96 offset:8
	v_xor_b32_e32 v97, 1, v103
	v_lshl_add_u32 v97, v97, 4, v94
	v_add_u32_e32 v98, s12, v97
	ds_read_b32 v99, v97
	ds_read_b32 v100, v97 offset:8
	ds_read_b32 v101, v98
	ds_read_b32 v102, v98 offset:8
	s_waitcnt lgkmcnt(4)
	v_mfma_f32_32x32x2_f32 v[0:15], v37, v130, 0
	v_mfma_f32_32x32x2_f32 v[46:61], v39, v194, 0
	v_mfma_f32_32x32x2_f32 v[0:15], v38, v131, v[0:15]
	v_mfma_f32_32x32x2_f32 v[46:61], v40, v195, v[46:61]
	v_xor_b32_e32 v95, 2, v103
	v_lshl_add_u32 v95, v95, 4, v94
	v_add_u32_e32 v96, s12, v95
	ds_read_b32 v37, v95
	ds_read_b32 v38, v95 offset:8
	ds_read_b32 v39, v96
	ds_read_b32 v40, v96 offset:8
	s_waitcnt lgkmcnt(4)
	v_mfma_f32_32x32x2_f32 v[0:15], v99, v132, v[0:15]
	v_mfma_f32_32x32x2_f32 v[46:61], v101, v196, v[46:61]
	v_mfma_f32_32x32x2_f32 v[0:15], v100, v133, v[0:15]
	v_mfma_f32_32x32x2_f32 v[46:61], v102, v197, v[46:61]
	v_xor_b32_e32 v97, 3, v103
	v_lshl_add_u32 v97, v97, 4, v94
	v_add_u32_e32 v98, s12, v97
	ds_read_b32 v99, v97
	ds_read_b32 v100, v97 offset:8
	ds_read_b32 v101, v98
	ds_read_b32 v102, v98 offset:8
	s_waitcnt lgkmcnt(4)
	v_mfma_f32_32x32x2_f32 v[0:15], v37, v134, v[0:15]
	v_mfma_f32_32x32x2_f32 v[46:61], v39, v198, v[46:61]
	v_mfma_f32_32x32x2_f32 v[0:15], v38, v135, v[0:15]
	v_mfma_f32_32x32x2_f32 v[46:61], v40, v199, v[46:61]
	v_xor_b32_e32 v95, 4, v103
	v_lshl_add_u32 v95, v95, 4, v94
	v_add_u32_e32 v96, s12, v95
	ds_read_b32 v37, v95
	ds_read_b32 v38, v95 offset:8
	ds_read_b32 v39, v96
	ds_read_b32 v40, v96 offset:8
	s_waitcnt lgkmcnt(4)
	v_mfma_f32_32x32x2_f32 v[0:15], v99, v136, v[0:15]
	v_mfma_f32_32x32x2_f32 v[46:61], v101, v204, v[46:61]
	v_mfma_f32_32x32x2_f32 v[0:15], v100, v137, v[0:15]
	v_mfma_f32_32x32x2_f32 v[46:61], v102, v205, v[46:61]
	v_xor_b32_e32 v97, 5, v103
	v_lshl_add_u32 v97, v97, 4, v94
	v_add_u32_e32 v98, s12, v97
	ds_read_b32 v99, v97
	ds_read_b32 v100, v97 offset:8
	ds_read_b32 v101, v98
	ds_read_b32 v102, v98 offset:8
	s_waitcnt lgkmcnt(4)
	v_mfma_f32_32x32x2_f32 v[0:15], v37, v138, v[0:15]
	v_mfma_f32_32x32x2_f32 v[46:61], v39, v206, v[46:61]
	v_mfma_f32_32x32x2_f32 v[0:15], v38, v139, v[0:15]
	v_mfma_f32_32x32x2_f32 v[46:61], v40, v207, v[46:61]
	v_xor_b32_e32 v95, 6, v103
	v_lshl_add_u32 v95, v95, 4, v94
	v_add_u32_e32 v96, s12, v95
	ds_read_b32 v37, v95
	ds_read_b32 v38, v95 offset:8
	ds_read_b32 v39, v96
	ds_read_b32 v40, v96 offset:8
	s_waitcnt lgkmcnt(4)
	v_mfma_f32_32x32x2_f32 v[0:15], v99, v140, v[0:15]
	v_mfma_f32_32x32x2_f32 v[46:61], v101, v208, v[46:61]
	v_mfma_f32_32x32x2_f32 v[0:15], v100, v141, v[0:15]
	v_mfma_f32_32x32x2_f32 v[46:61], v102, v209, v[46:61]
	v_xor_b32_e32 v97, 7, v103
	v_lshl_add_u32 v97, v97, 4, v94
	v_add_u32_e32 v98, s12, v97
	ds_read_b32 v99, v97
	ds_read_b32 v100, v97 offset:8
	ds_read_b32 v101, v98
	ds_read_b32 v102, v98 offset:8
	s_waitcnt lgkmcnt(4)
; __device__ __forceinline__ void phase_prep(const Params& P, int l, unsigned char* lds) {
;     ...
; #pragma unroll 2
;             for (int c = 0; c < 64; ++c) {
;                 float cv[4], sv[4];
; #pragma unroll
;                 for (int q = 0; q < 4; ++q) { const float rev = (float)((c * (cp0 + q)) & 63) * (1.0f / 64.0f); cv[q] = __builtin_amdgcn_cosf(rev) * 0.125f; sv[q] = __builtin_amdgcn_sinf(rev) * 0.125f; }
; #pragma unroll
;                 for (int t = 0; t < 8; ++t) { const float u = ub[t * 256 + c], u2 = ub2[t * 256 + c];
; #pragma unroll
;                     for (int q = 0; q < 4; ++q) { aC[q][t] += u * cv[q]; aS[q][t] += u2 * ((t == 0 && sp0) ? cv[q] : sv[q]); } }
;             }
	v_mfma_f32_32x32x2_f32 v[0:15], v37, v142, v[0:15]
	v_mfma_f32_32x32x2_f32 v[46:61], v39, v210, v[46:61]
	v_mfma_f32_32x32x2_f32 v[0:15], v38, v143, v[0:15]
	v_mfma_f32_32x32x2_f32 v[46:61], v40, v211, v[46:61]
	v_xor_b32_e32 v95, 8, v103
	v_lshl_add_u32 v95, v95, 4, v94
	v_add_u32_e32 v96, s12, v95
	ds_read_b32 v37, v95
	ds_read_b32 v38, v95 offset:8
	ds_read_b32 v39, v96
	ds_read_b32 v40, v96 offset:8
	s_waitcnt lgkmcnt(4)
	v_mfma_f32_32x32x2_f32 v[0:15], v99, v144, v[0:15]
	v_mfma_f32_32x32x2_f32 v[46:61], v101, v212, v[46:61]
	v_mfma_f32_32x32x2_f32 v[0:15], v100, v145, v[0:15]
	v_mfma_f32_32x32x2_f32 v[46:61], v102, v213, v[46:61]
	v_xor_b32_e32 v97, 9, v103
	v_lshl_add_u32 v97, v97, 4, v94
	v_add_u32_e32 v98, s12, v97
	ds_read_b32 v99, v97
	ds_read_b32 v100, v97 offset:8
	ds_read_b32 v101, v98
	ds_read_b32 v102, v98 offset:8
	s_waitcnt lgkmcnt(4)
	v_mfma_f32_32x32x2_f32 v[0:15], v37, v146, v[0:15]
	v_mfma_f32_32x32x2_f32 v[46:61], v39, v214, v[46:61]
	v_mfma_f32_32x32x2_f32 v[0:15], v38, v147, v[0:15]
	v_mfma_f32_32x32x2_f32 v[46:61], v40, v215, v[46:61]
	v_xor_b32_e32 v95, 10, v103
	v_lshl_add_u32 v95, v95, 4, v94
	v_add_u32_e32 v96, s12, v95
	ds_read_b32 v37, v95
	ds_read_b32 v38, v95 offset:8
	ds_read_b32 v39, v96
	ds_read_b32 v40, v96 offset:8
	s_waitcnt lgkmcnt(4)
	v_mfma_f32_32x32x2_f32 v[0:15], v99, v148, v[0:15]
	v_mfma_f32_32x32x2_f32 v[46:61], v101, v216, v[46:61]
	v_mfma_f32_32x32x2_f32 v[0:15], v100, v149, v[0:15]
	v_mfma_f32_32x32x2_f32 v[46:61], v102, v217, v[46:61]
	v_xor_b32_e32 v97, 11, v103
	v_lshl_add_u32 v97, v97, 4, v94
	v_add_u32_e32 v98, s12, v97
	ds_read_b32 v99, v97
	ds_read_b32 v100, v97 offset:8
	ds_read_b32 v101, v98
	ds_read_b32 v102, v98 offset:8
	s_waitcnt lgkmcnt(4)
	v_mfma_f32_32x32x2_f32 v[0:15], v37, v150, v[0:15]
	v_mfma_f32_32x32x2_f32 v[46:61], v39, v218, v[46:61]
	v_mfma_f32_32x32x2_f32 v[0:15], v38, v151, v[0:15]
	v_mfma_f32_32x32x2_f32 v[46:61], v40, v219, v[46:61]
	v_xor_b32_e32 v95, 12, v103
	v_lshl_add_u32 v95, v95, 4, v94
	v_add_u32_e32 v96, s12, v95
	ds_read_b32 v37, v95
	ds_read_b32 v38, v95 offset:8
	ds_read_b32 v39, v96
	ds_read_b32 v40, v96 offset:8
	s_waitcnt lgkmcnt(4)
	v_mfma_f32_32x32x2_f32 v[0:15], v99, v152, v[0:15]
	v_mfma_f32_32x32x2_f32 v[46:61], v101, v220, v[46:61]
	v_mfma_f32_32x32x2_f32 v[0:15], v100, v153, v[0:15]
	v_mfma_f32_32x32x2_f32 v[46:61], v102, v221, v[46:61]
	v_xor_b32_e32 v97, 13, v103
	v_lshl_add_u32 v97, v97, 4, v94
	v_add_u32_e32 v98, s12, v97
	ds_read_b32 v99, v97
	ds_read_b32 v100, v97 offset:8
	ds_read_b32 v101, v98
	ds_read_b32 v102, v98 offset:8
	s_waitcnt lgkmcnt(4)
	v_mfma_f32_32x32x2_f32 v[0:15], v37, v154, v[0:15]
	v_mfma_f32_32x32x2_f32 v[46:61], v39, v222, v[46:61]
	v_mfma_f32_32x32x2_f32 v[0:15], v38, v155, v[0:15]
	v_mfma_f32_32x32x2_f32 v[46:61], v40, v223, v[46:61]
	v_xor_b32_e32 v95, 14, v103
	v_lshl_add_u32 v95, v95, 4, v94
	v_add_u32_e32 v96, s12, v95
	ds_read_b32 v37, v95
	ds_read_b32 v38, v95 offset:8
	ds_read_b32 v39, v96
	ds_read_b32 v40, v96 offset:8
	s_waitcnt lgkmcnt(4)
	v_mfma_f32_32x32x2_f32 v[0:15], v99, v156, v[0:15]
	v_mfma_f32_32x32x2_f32 v[46:61], v101, v224, v[46:61]
	v_mfma_f32_32x32x2_f32 v[0:15], v100, v157, v[0:15]
	v_mfma_f32_32x32x2_f32 v[46:61], v102, v225, v[46:61]
	v_xor_b32_e32 v97, 15, v103
	v_lshl_add_u32 v97, v97, 4, v94
	v_add_u32_e32 v98, s12, v97
	ds_read_b32 v99, v97
	ds_read_b32 v100, v97 offset:8
	ds_read_b32 v101, v98
	ds_read_b32 v102, v98 offset:8
	s_waitcnt lgkmcnt(4)
	v_mfma_f32_32x32x2_f32 v[0:15], v37, v158, v[0:15]
	v_mfma_f32_32x32x2_f32 v[46:61], v39, v226, v[46:61]
	v_mfma_f32_32x32x2_f32 v[0:15], v38, v159, v[0:15]
	v_mfma_f32_32x32x2_f32 v[46:61], v40, v227, v[46:61]
	s_waitcnt lgkmcnt(0)
	v_mfma_f32_32x32x2_f32 v[0:15], v99, v160, v[0:15]
	v_mfma_f32_32x32x2_f32 v[46:61], v101, v228, v[46:61]
	v_mfma_f32_32x32x2_f32 v[0:15], v100, v161, v[0:15]
	v_mfma_f32_32x32x2_f32 v[46:61], v102, v229, v[46:61]
	v_lshl_add_u32 v41, v34, 10, s7
	v_lshlrev_b32_e32 v42, 3, v33
	v_xor_b32_e32 v42, v42, v103
	v_xor_b32_e32 v43, 0, v42
	v_lshl_add_u32 v43, v43, 4, v41
	ds_read_b128 v[110:113], v43
	s_waitcnt lgkmcnt(0)
	v_sub_f32_e32 v104, v110, v111
	v_add_f32_e32 v104, v104, v112
	v_sub_f32_e32 v104, v104, v113
	v_xor_b32_e32 v43, 1, v42
	v_lshl_add_u32 v43, v43, 4, v41
	ds_read_b128 v[110:113], v43
	s_waitcnt lgkmcnt(0)
	v_add_f32_e32 v104, v104, v110
	v_sub_f32_e32 v104, v104, v111
	v_add_f32_e32 v104, v104, v112
	v_sub_f32_e32 v104, v104, v113
	v_xor_b32_e32 v43, 2, v42
	v_lshl_add_u32 v43, v43, 4, v41
	ds_read_b128 v[110:113], v43
	s_waitcnt lgkmcnt(0)
	v_add_f32_e32 v104, v104, v110
	v_sub_f32_e32 v104, v104, v111
	v_add_f32_e32 v104, v104, v112
	v_sub_f32_e32 v104, v104, v113
	v_xor_b32_e32 v43, 3, v42
	v_lshl_add_u32 v43, v43, 4, v41
	ds_read_b128 v[110:113], v43
	s_waitcnt lgkmcnt(0)
	v_add_f32_e32 v104, v104, v110
	v_sub_f32_e32 v104, v104, v111
	v_add_f32_e32 v104, v104, v112
	v_sub_f32_e32 v104, v104, v113
	v_xor_b32_e32 v43, 4, v42
	v_lshl_add_u32 v43, v43, 4, v41
	ds_read_b128 v[110:113], v43
	s_waitcnt lgkmcnt(0)
	v_add_f32_e32 v104, v104, v110
	v_sub_f32_e32 v104, v104, v111
	v_add_f32_e32 v104, v104, v112
	v_sub_f32_e32 v104, v104, v113
	v_xor_b32_e32 v43, 5, v42
	v_lshl_add_u32 v43, v43, 4, v41
	ds_read_b128 v[110:113], v43
	s_waitcnt lgkmcnt(0)
	v_add_f32_e32 v104, v104, v110
	v_sub_f32_e32 v104, v104, v111
	v_add_f32_e32 v104, v104, v112
	v_sub_f32_e32 v104, v104, v113
	v_xor_b32_e32 v43, 6, v42
	v_lshl_add_u32 v43, v43, 4, v41
	ds_read_b128 v[110:113], v43
	s_waitcnt lgkmcnt(0)
	v_add_f32_e32 v104, v104, v110
	v_sub_f32_e32 v104, v104, v111
	v_add_f32_e32 v104, v104, v112
	v_sub_f32_e32 v104, v104, v113
	v_xor_b32_e32 v43, 7, v42
	v_lshl_add_u32 v43, v43, 4, v41
	ds_read_b128 v[110:113], v43
	s_waitcnt lgkmcnt(0)
	v_add_f32_e32 v104, v104, v110
	v_sub_f32_e32 v104, v104, v111
	v_add_f32_e32 v104, v104, v112
	v_sub_f32_e32 v104, v104, v113
	v_xor_b32_e32 v43, 32, v32
	v_lshlrev_b32_e32 v43, 2, v43
	ds_bpermute_b32 v110, v43, v104
	s_waitcnt lgkmcnt(0)
	v_add_f32_e32 v104, v104, v110
	v_mul_f32_e32 v104, 0x3e000000, v104
	v_cvt_pk_bf16_f32 v104, v104, v104
	s_mov_b32 s19, 0
	s_cmp_eq_u32 s64, 0x100
	s_cbranch_scc0 .Ldft_nosp
; __device__ __forceinline__ void phase_prep(const Params& P, int l, unsigned char* lds) {
;     ...
;                 for (int t = 0; t < 8; ++t) { const float u = ub[t * 256 + c], u2 = ub2[t * 256 + c];
; #pragma unroll
;                     for (int q = 0; q < 4; ++q) { aC[q][t] += u * cv[q]; aS[q][t] += u2 * ((t == 0 && sp0) ? cv[q] : sv[q]); } }
;             }
	s_cmp_eq_u32 s13, 0
	s_cbranch_scc0 .Ldft_nosp
	s_mov_b32 s19, 1
	v_xor_b32_e32 v95, 0, v103
	v_lshl_add_u32 v95, v95, 4, v94
	v_add_u32_e32 v96, 0x10000, v95
	ds_read_b32 v39, v96
	ds_read_b32 v40, v96 offset:8
	s_waitcnt lgkmcnt(0)
	v_mfma_f32_32x32x2_f32 v[78:93], v39, v130, 0
	v_mfma_f32_32x32x2_f32 v[78:93], v40, v131, v[78:93]
	v_xor_b32_e32 v95, 1, v103
	v_lshl_add_u32 v95, v95, 4, v94
	v_add_u32_e32 v96, 0x10000, v95
	ds_read_b32 v39, v96
	ds_read_b32 v40, v96 offset:8
	s_waitcnt lgkmcnt(0)
	v_mfma_f32_32x32x2_f32 v[78:93], v39, v132, v[78:93]
	v_mfma_f32_32x32x2_f32 v[78:93], v40, v133, v[78:93]
	v_xor_b32_e32 v95, 2, v103
	v_lshl_add_u32 v95, v95, 4, v94
	v_add_u32_e32 v96, 0x10000, v95
	ds_read_b32 v39, v96
	ds_read_b32 v40, v96 offset:8
	s_waitcnt lgkmcnt(0)
	v_mfma_f32_32x32x2_f32 v[78:93], v39, v134, v[78:93]
	v_mfma_f32_32x32x2_f32 v[78:93], v40, v135, v[78:93]
	v_xor_b32_e32 v95, 3, v103
	v_lshl_add_u32 v95, v95, 4, v94
	v_add_u32_e32 v96, 0x10000, v95
	ds_read_b32 v39, v96
	ds_read_b32 v40, v96 offset:8
	s_waitcnt lgkmcnt(0)
	v_mfma_f32_32x32x2_f32 v[78:93], v39, v136, v[78:93]
	v_mfma_f32_32x32x2_f32 v[78:93], v40, v137, v[78:93]
	v_xor_b32_e32 v95, 4, v103
	v_lshl_add_u32 v95, v95, 4, v94
	v_add_u32_e32 v96, 0x10000, v95
	ds_read_b32 v39, v96
	ds_read_b32 v40, v96 offset:8
	s_waitcnt lgkmcnt(0)
	v_mfma_f32_32x32x2_f32 v[78:93], v39, v138, v[78:93]
	v_mfma_f32_32x32x2_f32 v[78:93], v40, v139, v[78:93]
	v_xor_b32_e32 v95, 5, v103
	v_lshl_add_u32 v95, v95, 4, v94
	v_add_u32_e32 v96, 0x10000, v95
	ds_read_b32 v39, v96
	ds_read_b32 v40, v96 offset:8
	s_waitcnt lgkmcnt(0)
	v_mfma_f32_32x32x2_f32 v[78:93], v39, v140, v[78:93]
	v_mfma_f32_32x32x2_f32 v[78:93], v40, v141, v[78:93]
	v_xor_b32_e32 v95, 6, v103
	v_lshl_add_u32 v95, v95, 4, v94
	v_add_u32_e32 v96, 0x10000, v95
	ds_read_b32 v39, v96
	ds_read_b32 v40, v96 offset:8
	s_waitcnt lgkmcnt(0)
	v_mfma_f32_32x32x2_f32 v[78:93], v39, v142, v[78:93]
	v_mfma_f32_32x32x2_f32 v[78:93], v40, v143, v[78:93]
	v_xor_b32_e32 v95, 7, v103
	v_lshl_add_u32 v95, v95, 4, v94
	v_add_u32_e32 v96, 0x10000, v95
	ds_read_b32 v39, v96
	ds_read_b32 v40, v96 offset:8
	s_waitcnt lgkmcnt(0)
	v_mfma_f32_32x32x2_f32 v[78:93], v39, v144, v[78:93]
	v_mfma_f32_32x32x2_f32 v[78:93], v40, v145, v[78:93]
	v_xor_b32_e32 v95, 8, v103
	v_lshl_add_u32 v95, v95, 4, v94
	v_add_u32_e32 v96, 0x10000, v95
	ds_read_b32 v39, v96
	ds_read_b32 v40, v96 offset:8
	s_waitcnt lgkmcnt(0)
	v_mfma_f32_32x32x2_f32 v[78:93], v39, v146, v[78:93]
	v_mfma_f32_32x32x2_f32 v[78:93], v40, v147, v[78:93]
	v_xor_b32_e32 v95, 9, v103
	v_lshl_add_u32 v95, v95, 4, v94
	v_add_u32_e32 v96, 0x10000, v95
	ds_read_b32 v39, v96
	ds_read_b32 v40, v96 offset:8
	s_waitcnt lgkmcnt(0)
	v_mfma_f32_32x32x2_f32 v[78:93], v39, v148, v[78:93]
	v_mfma_f32_32x32x2_f32 v[78:93], v40, v149, v[78:93]
	v_xor_b32_e32 v95, 10, v103
	v_lshl_add_u32 v95, v95, 4, v94
	v_add_u32_e32 v96, 0x10000, v95
	ds_read_b32 v39, v96
	ds_read_b32 v40, v96 offset:8
	s_waitcnt lgkmcnt(0)
	v_mfma_f32_32x32x2_f32 v[78:93], v39, v150, v[78:93]
	v_mfma_f32_32x32x2_f32 v[78:93], v40, v151, v[78:93]
	v_xor_b32_e32 v95, 11, v103
	v_lshl_add_u32 v95, v95, 4, v94
	v_add_u32_e32 v96, 0x10000, v95
	ds_read_b32 v39, v96
	ds_read_b32 v40, v96 offset:8
	s_waitcnt lgkmcnt(0)
	v_mfma_f32_32x32x2_f32 v[78:93], v39, v152, v[78:93]
	v_mfma_f32_32x32x2_f32 v[78:93], v40, v153, v[78:93]
	v_xor_b32_e32 v95, 12, v103
	v_lshl_add_u32 v95, v95, 4, v94
	v_add_u32_e32 v96, 0x10000, v95
	ds_read_b32 v39, v96
	ds_read_b32 v40, v96 offset:8
	s_waitcnt lgkmcnt(0)
	v_mfma_f32_32x32x2_f32 v[78:93], v39, v154, v[78:93]
	v_mfma_f32_32x32x2_f32 v[78:93], v40, v155, v[78:93]
	v_xor_b32_e32 v95, 13, v103
	v_lshl_add_u32 v95, v95, 4, v94
	v_add_u32_e32 v96, 0x10000, v95
	ds_read_b32 v39, v96
	ds_read_b32 v40, v96 offset:8
	s_waitcnt lgkmcnt(0)
	v_mfma_f32_32x32x2_f32 v[78:93], v39, v156, v[78:93]
	v_mfma_f32_32x32x2_f32 v[78:93], v40, v157, v[78:93]
	v_xor_b32_e32 v95, 14, v103
	v_lshl_add_u32 v95, v95, 4, v94
	v_add_u32_e32 v96, 0x10000, v95
	ds_read_b32 v39, v96
	ds_read_b32 v40, v96 offset:8
	s_waitcnt lgkmcnt(0)
	v_mfma_f32_32x32x2_f32 v[78:93], v39, v158, v[78:93]
	v_mfma_f32_32x32x2_f32 v[78:93], v40, v159, v[78:93]
	v_xor_b32_e32 v95, 15, v103
	v_lshl_add_u32 v95, v95, 4, v94
	v_add_u32_e32 v96, 0x10000, v95
	ds_read_b32 v39, v96
	ds_read_b32 v40, v96 offset:8
	s_waitcnt lgkmcnt(0)
	v_mfma_f32_32x32x2_f32 v[78:93], v39, v160, v[78:93]
	v_mfma_f32_32x32x2_f32 v[78:93], v40, v161, v[78:93]
	v_lshl_add_u32 v41, v34, 10, s7
	v_add_u32_e32 v41, 0x10000, v41
	v_lshlrev_b32_e32 v42, 3, v33
	v_xor_b32_e32 v42, v42, v103
	v_xor_b32_e32 v43, 0, v42
	v_lshl_add_u32 v43, v43, 4, v41
	ds_read_b128 v[110:113], v43
	s_waitcnt lgkmcnt(0)
	v_sub_f32_e32 v105, v110, v111
	v_add_f32_e32 v105, v105, v112
	v_sub_f32_e32 v105, v105, v113
	v_xor_b32_e32 v43, 1, v42
	v_lshl_add_u32 v43, v43, 4, v41
	ds_read_b128 v[110:113], v43
	s_waitcnt lgkmcnt(0)
	v_add_f32_e32 v105, v105, v110
	v_sub_f32_e32 v105, v105, v111
	v_add_f32_e32 v105, v105, v112
	v_sub_f32_e32 v105, v105, v113
	v_xor_b32_e32 v43, 2, v42
	v_lshl_add_u32 v43, v43, 4, v41
	ds_read_b128 v[110:113], v43
	s_waitcnt lgkmcnt(0)
	v_add_f32_e32 v105, v105, v110
	v_sub_f32_e32 v105, v105, v111
	v_add_f32_e32 v105, v105, v112
	v_sub_f32_e32 v105, v105, v113
	v_xor_b32_e32 v43, 3, v42
	v_lshl_add_u32 v43, v43, 4, v41
	ds_read_b128 v[110:113], v43
	s_waitcnt lgkmcnt(0)
	v_add_f32_e32 v105, v105, v110
	v_sub_f32_e32 v105, v105, v111
	v_add_f32_e32 v105, v105, v112
	v_sub_f32_e32 v105, v105, v113
	v_xor_b32_e32 v43, 4, v42
	v_lshl_add_u32 v43, v43, 4, v41
	ds_read_b128 v[110:113], v43
	s_waitcnt lgkmcnt(0)
	v_add_f32_e32 v105, v105, v110
	v_sub_f32_e32 v105, v105, v111
	v_add_f32_e32 v105, v105, v112
	v_sub_f32_e32 v105, v105, v113
	v_xor_b32_e32 v43, 5, v42
	v_lshl_add_u32 v43, v43, 4, v41
	ds_read_b128 v[110:113], v43
	s_waitcnt lgkmcnt(0)
	v_add_f32_e32 v105, v105, v110
	v_sub_f32_e32 v105, v105, v111
	v_add_f32_e32 v105, v105, v112
	v_sub_f32_e32 v105, v105, v113
	v_xor_b32_e32 v43, 6, v42
	v_lshl_add_u32 v43, v43, 4, v41
	ds_read_b128 v[110:113], v43
	s_waitcnt lgkmcnt(0)
	v_add_f32_e32 v105, v105, v110
	v_sub_f32_e32 v105, v105, v111
	v_add_f32_e32 v105, v105, v112
	v_sub_f32_e32 v105, v105, v113
	v_xor_b32_e32 v43, 7, v42
	v_lshl_add_u32 v43, v43, 4, v41
	ds_read_b128 v[110:113], v43
	s_waitcnt lgkmcnt(0)
	v_add_f32_e32 v105, v105, v110
	v_sub_f32_e32 v105, v105, v111
	v_add_f32_e32 v105, v105, v112
	v_sub_f32_e32 v105, v105, v113
	v_xor_b32_e32 v43, 32, v32
	v_lshlrev_b32_e32 v43, 2, v43
	ds_bpermute_b32 v110, v43, v105
	s_waitcnt lgkmcnt(0)
	v_add_f32_e32 v105, v105, v110
	v_mul_f32_e32 v105, 0x3e000000, v105
	v_cvt_pk_bf16_f32 v105, v105, v105
; __device__ __forceinline__ unsigned pk2(float lo, float hi) { f32x2_t v = {lo, hi}; bf16x2_t b = __builtin_convertvector(v, bf16x2_t); return __builtin_bit_cast(unsigned, b); }
; __device__ __forceinline__ void phase_prep(const Params& P, int l, unsigned char* lds) {
;     ...
; #pragma unroll
;             for (int q = 0; q < 4; ++q) {
;                 const int n = n0 + q;
;                 bf16_t* dC; bf16_t* dS;
;                 if (is_ctx) { bf16_t* z = (bf16_t*)(P.ws + WS_ZCT) + ((size_t)b * 256 + n) * 512 + t0 + t8; dC = z; dS = z + 256; }
;                 else { bf16_t* z = (bf16_t*)(P.ws + WS_ZT) + ((size_t)b * 256 + n) * 2048 + (t0 - CTX) + t8; dC = z; dS = z + 1024; }
;                 u32x4 o; o.x = pk2(aC[q][0], aC[q][1]); o.y = pk2(aC[q][2], aC[q][3]); o.z = pk2(aC[q][4], aC[q][5]); o.w = pk2(aC[q][6], aC[q][7]);
;                 *(u32x4*)dC = o;
;                 u32x4 s4; s4.x = pk2(aS[q][0], aS[q][1]); s4.y = pk2(aS[q][2], aS[q][3]); s4.z = pk2(aS[q][4], aS[q][5]); s4.w = pk2(aS[q][6], aS[q][7]);
;                 *(u32x4*)dS = s4;
;             }
.Ldft_nosp:
	s_nop 15
	s_nop 7
	v_cvt_pk_bf16_f32 v16, v0, v1
	v_cvt_pk_bf16_f32 v17, v2, v3
	v_cvt_pk_bf16_f32 v18, v4, v5
	v_cvt_pk_bf16_f32 v19, v6, v7
	v_cvt_pk_bf16_f32 v20, v8, v9
	v_cvt_pk_bf16_f32 v21, v10, v11
	v_cvt_pk_bf16_f32 v22, v12, v13
	v_cvt_pk_bf16_f32 v23, v14, v15
	v_cvt_pk_bf16_f32 v24, v46, v47
	v_cvt_pk_bf16_f32 v25, v48, v49
	v_cvt_pk_bf16_f32 v26, v50, v51
	v_cvt_pk_bf16_f32 v27, v52, v53
	v_cvt_pk_bf16_f32 v28, v54, v55
	v_cvt_pk_bf16_f32 v29, v56, v57
	v_cvt_pk_bf16_f32 v30, v58, v59
	v_cvt_pk_bf16_f32 v31, v60, v61
	v_cvt_pk_bf16_f32 v78, v78, v78
	s_and_b64 vcc, exec, s[42:43]
	s_cbranch_vccz .Ldft_out_ctx
	s_lshl_b32 s7, s36, 8
	s_lshl_b32 s18, s15, 6
	s_add_u32 s7, s7, s18
	s_mul_i32 s7, s7, 4096
	s_sub_u32 s18, s64, 256
	s_lshl_b32 s12, s13, 5
	s_add_u32 s18, s18, s12
	s_lshl_b32 s18, s18, 1
	s_add_u32 s7, s7, s18
	s_add_u32 s40, s0, s7
	s_addc_u32 s41, s1, 0
	s_add_u32 s40, s40, 0x17e00000
	s_addc_u32 s41, s41, 0
	v_lshlrev_b32_e32 v124, 12, v34
	v_lshl_add_u32 v124, v33, 3, v124
	v_sub_u32_e32 v125, 64, v34
	v_lshlrev_b32_e32 v125, 12, v125
	v_lshl_add_u32 v125, v33, 3, v125
	v_lshlrev_b32_e32 v41, 1, v34
	v_add_u32_e32 v41, 0x20000, v41
	global_store_dwordx2 v124, v[16:17], s[40:41]
	global_store_dwordx2 v124, v[18:19], s[40:41] offset:16
	global_store_dwordx2 v124, v[20:21], s[40:41] offset:32
	global_store_dwordx2 v124, v[22:23], s[40:41] offset:48
	global_store_dwordx2 v124, v[24:25], s[40:41] offset:2048
	global_store_dwordx2 v124, v[26:27], s[40:41] offset:2064
	global_store_dwordx2 v124, v[28:29], s[40:41] offset:2080
	global_store_dwordx2 v124, v[30:31], s[40:41] offset:2096
	v_cmp_gt_u32_e32 vcc, 32, v32
	s_and_saveexec_b64 s[50:51], vcc
	global_store_short v41, v104, s[40:41]
	global_store_short v41, v129, s[40:41] offset:2048
	s_or_b64 exec, exec, s[50:51]
	v_xor_b32_e32 v24, 0x80008000, v24
	v_xor_b32_e32 v25, 0x80008000, v25
	v_xor_b32_e32 v26, 0x80008000, v26
	v_xor_b32_e32 v27, 0x80008000, v27
	v_xor_b32_e32 v28, 0x80008000, v28
	v_xor_b32_e32 v29, 0x80008000, v29
	v_xor_b32_e32 v30, 0x80008000, v30
	v_xor_b32_e32 v31, 0x80008000, v31
	v_cmp_ne_u32_e32 vcc, 0, v34
	s_and_saveexec_b64 s[50:51], vcc
	global_store_dwordx2 v125, v[16:17], s[40:41]
	global_store_dwordx2 v125, v[18:19], s[40:41] offset:16
	global_store_dwordx2 v125, v[20:21], s[40:41] offset:32
	global_store_dwordx2 v125, v[22:23], s[40:41] offset:48
	global_store_dwordx2 v125, v[24:25], s[40:41] offset:2048
	global_store_dwordx2 v125, v[26:27], s[40:41] offset:2064
	global_store_dwordx2 v125, v[28:29], s[40:41] offset:2080
	global_store_dwordx2 v125, v[30:31], s[40:41] offset:2096
	s_or_b64 exec, exec, s[50:51]
	s_cmp_eq_u32 s19, 0
	s_cbranch_scc1 .Ldft_fix_lat
	v_lshlrev_b32_e32 v42, 12, v34
	v_sub_u32_e32 v43, 64, v34
	v_lshlrev_b32_e32 v43, 12, v43
	v_cmp_gt_u32_e32 vcc, 32, v32
	s_and_saveexec_b64 s[50:51], vcc
	global_store_short v42, v78, s[40:41] offset:2048
	v_cmp_ne_u32_e32 vcc, 0, v34
	s_and_b64 exec, exec, vcc
	global_store_short v43, v78, s[40:41] offset:2048
	s_or_b64 exec, exec, s[50:51]
	v_cmp_eq_u32_e32 vcc, 0, v32
	s_and_saveexec_b64 s[50:51], vcc
	v_mov_b32_e32 v42, 0x20000
	global_store_short v42, v105, s[40:41] offset:2048
	s_or_b64 exec, exec, s[50:51]

; __device__ __forceinline__ unsigned pk2(float lo, float hi) { f32x2_t v = {lo, hi}; bf16x2_t b = __builtin_convertvector(v, bf16x2_t); return __builtin_bit_cast(unsigned, b); }
; __device__ __forceinline__ void phase_prep(const Params& P, int l, unsigned char* lds) {
;     ...
; #pragma unroll
;             for (int q = 0; q < 4; ++q) {
;                 const int n = n0 + q;
;                 bf16_t* dC; bf16_t* dS;
;                 if (is_ctx) { bf16_t* z = (bf16_t*)(P.ws + WS_ZCT) + ((size_t)b * 256 + n) * 512 + t0 + t8; dC = z; dS = z + 256; }
;                 else { bf16_t* z = (bf16_t*)(P.ws + WS_ZT) + ((size_t)b * 256 + n) * 2048 + (t0 - CTX) + t8; dC = z; dS = z + 1024; }
;                 u32x4 o; o.x = pk2(aC[q][0], aC[q][1]); o.y = pk2(aC[q][2], aC[q][3]); o.z = pk2(aC[q][4], aC[q][5]); o.w = pk2(aC[q][6], aC[q][7]);
;                 *(u32x4*)dC = o;
;                 u32x4 s4; s4.x = pk2(aS[q][0], aS[q][1]); s4.y = pk2(aS[q][2], aS[q][3]); s4.z = pk2(aS[q][4], aS[q][5]); s4.w = pk2(aS[q][6], aS[q][7]);
;                 *(u32x4*)dS = s4;
;             }
.Ldft_out_ctx:
	s_lshl_b32 s7, s36, 8
	s_lshl_b32 s18, s15, 6
	s_add_u32 s7, s7, s18
	s_mul_i32 s7, s7, 1024
	s_sub_u32 s18, s64, 0
	s_lshl_b32 s12, s13, 5
	s_add_u32 s18, s18, s12
	s_lshl_b32 s18, s18, 1
	s_add_u32 s7, s7, s18
	s_add_u32 s40, s0, s7
	s_addc_u32 s41, s1, 0
	s_add_u32 s40, s40, 0x19e00000
	s_addc_u32 s41, s41, 0
	v_lshlrev_b32_e32 v124, 10, v34
	v_lshl_add_u32 v124, v33, 3, v124
	v_sub_u32_e32 v125, 64, v34
	v_lshlrev_b32_e32 v125, 10, v125
	v_lshl_add_u32 v125, v33, 3, v125
	v_lshlrev_b32_e32 v41, 1, v34
	v_add_u32_e32 v41, 0x8000, v41
	global_store_dwordx2 v124, v[16:17], s[40:41]
	global_store_dwordx2 v124, v[18:19], s[40:41] offset:16
	global_store_dwordx2 v124, v[20:21], s[40:41] offset:32
	global_store_dwordx2 v124, v[22:23], s[40:41] offset:48
	global_store_dwordx2 v124, v[24:25], s[40:41] offset:512
	global_store_dwordx2 v124, v[26:27], s[40:41] offset:528
	global_store_dwordx2 v124, v[28:29], s[40:41] offset:544
	global_store_dwordx2 v124, v[30:31], s[40:41] offset:560
	v_cmp_gt_u32_e32 vcc, 32, v32
	s_and_saveexec_b64 s[50:51], vcc
	global_store_short v41, v104, s[40:41]
	global_store_short v41, v129, s[40:41] offset:512
	s_or_b64 exec, exec, s[50:51]
	v_xor_b32_e32 v24, 0x80008000, v24
	v_xor_b32_e32 v25, 0x80008000, v25
	v_xor_b32_e32 v26, 0x80008000, v26
	v_xor_b32_e32 v27, 0x80008000, v27
	v_xor_b32_e32 v28, 0x80008000, v28
	v_xor_b32_e32 v29, 0x80008000, v29
	v_xor_b32_e32 v30, 0x80008000, v30
	v_xor_b32_e32 v31, 0x80008000, v31
	v_cmp_ne_u32_e32 vcc, 0, v34
	s_and_saveexec_b64 s[50:51], vcc
	global_store_dwordx2 v125, v[16:17], s[40:41]
	global_store_dwordx2 v125, v[18:19], s[40:41] offset:16
	global_store_dwordx2 v125, v[20:21], s[40:41] offset:32
	global_store_dwordx2 v125, v[22:23], s[40:41] offset:48
	global_store_dwordx2 v125, v[24:25], s[40:41] offset:512
	global_store_dwordx2 v125, v[26:27], s[40:41] offset:528
	global_store_dwordx2 v125, v[28:29], s[40:41] offset:544
	global_store_dwordx2 v125, v[30:31], s[40:41] offset:560
	s_or_b64 exec, exec, s[50:51]
	s_cmp_eq_u32 s19, 0
	s_cbranch_scc1 .Ldft_fix_ctx
	v_lshlrev_b32_e32 v42, 10, v34
	v_sub_u32_e32 v43, 64, v34
	v_lshlrev_b32_e32 v43, 10, v43
	v_cmp_gt_u32_e32 vcc, 32, v32
	s_and_saveexec_b64 s[50:51], vcc
	global_store_short v42, v78, s[40:41] offset:512
	v_cmp_ne_u32_e32 vcc, 0, v34
	s_and_b64 exec, exec, vcc
	global_store_short v43, v78, s[40:41] offset:512
	s_or_b64 exec, exec, s[50:51]
	v_cmp_eq_u32_e32 vcc, 0, v32
	s_and_saveexec_b64 s[50:51], vcc
	v_mov_b32_e32 v42, 0x8000
	global_store_short v42, v105, s[40:41] offset:512
	s_or_b64 exec, exec, s[50:51]
